# g2 chunk-state scan rewritten: 8-chunk batches, two register sets, counted vmcnt (deeper prefetch)
# speedup vs baseline: 1.0190x; 1.0190x over previous
.LBB0_1200:
	v_lshlrev_b32_e32 v2, 1, v1
	v_and_b32_e32 v10, 0x7e, v2
	s_waitcnt vmcnt(0)
	v_ashrrev_i32_e32 v9, 14, v1
	v_bfe_u32 v8, v1, 6, 8
	v_lshlrev_b32_e32 v2, 2, v10
	v_and_b32_e32 v7, 3, v9
	v_lshl_or_b32 v6, v8, 7, v10
	v_lshl_add_u64 v[4:5], s[8:9], 0, v[2:3]
	v_ashrrev_i32_e32 v2, 16, v1
	v_lshl_or_b32 v2, v2, 9, v7
	s_mov_b32 s16, 0
	v_lshlrev_b32_e32 v11, 1, v6
	v_mov_b32_e32 v6, 0
	v_mov_b32_e32 v7, v3
	v_lshlrev_b32_e32 v12, 16, v2
	v_or_b32_e32 v12, v12, v11
	v_mov_b32_e32 v13, v12
	v_lshlrev_b32_e32 v14, 9, v2
	v_lshl_add_u32 v14, v10, 2, v14
	s_mov_b32 s16, 0
	global_load_dword v16, v12, s[4:5]
	global_load_dwordx2 v[24:25], v14, s[8:9]
	v_add_u32_e32 v12, 0x40000, v12
	v_add_u32_e32 v14, 0x800, v14
	global_load_dword v17, v12, s[4:5]
	global_load_dwordx2 v[26:27], v14, s[8:9]
	v_add_u32_e32 v12, 0x40000, v12
	v_add_u32_e32 v14, 0x800, v14
	global_load_dword v18, v12, s[4:5]
	global_load_dwordx2 v[28:29], v14, s[8:9]
	v_add_u32_e32 v12, 0x40000, v12
	v_add_u32_e32 v14, 0x800, v14
	global_load_dword v19, v12, s[4:5]
	global_load_dwordx2 v[30:31], v14, s[8:9]
	v_add_u32_e32 v12, 0x40000, v12
	v_add_u32_e32 v14, 0x800, v14
	global_load_dword v20, v12, s[4:5]
	global_load_dwordx2 v[32:33], v14, s[8:9]
	v_add_u32_e32 v12, 0x40000, v12
	v_add_u32_e32 v14, 0x800, v14
	global_load_dword v21, v12, s[4:5]
	global_load_dwordx2 v[34:35], v14, s[8:9]
	v_add_u32_e32 v12, 0x40000, v12
	v_add_u32_e32 v14, 0x800, v14
	global_load_dword v22, v12, s[4:5]
	global_load_dwordx2 v[36:37], v14, s[8:9]
	v_add_u32_e32 v12, 0x40000, v12
	v_add_u32_e32 v14, 0x800, v14
	global_load_dword v23, v12, s[4:5]
	global_load_dwordx2 v[38:39], v14, s[8:9]
	v_add_u32_e32 v12, 0x40000, v12
	v_add_u32_e32 v14, 0x800, v14
.Lg2_loop:
	global_load_dword v40, v12, s[4:5]
	global_load_dwordx2 v[48:49], v14, s[8:9]
	v_add_u32_e32 v12, 0x40000, v12
	v_add_u32_e32 v14, 0x800, v14
	global_load_dword v41, v12, s[4:5]
	global_load_dwordx2 v[50:51], v14, s[8:9]
	v_add_u32_e32 v12, 0x40000, v12
	v_add_u32_e32 v14, 0x800, v14
	global_load_dword v42, v12, s[4:5]
	global_load_dwordx2 v[52:53], v14, s[8:9]
	v_add_u32_e32 v12, 0x40000, v12
	v_add_u32_e32 v14, 0x800, v14
	global_load_dword v43, v12, s[4:5]
	global_load_dwordx2 v[54:55], v14, s[8:9]
	v_add_u32_e32 v12, 0x40000, v12
	v_add_u32_e32 v14, 0x800, v14
	global_load_dword v44, v12, s[4:5]
	global_load_dwordx2 v[56:57], v14, s[8:9]
	v_add_u32_e32 v12, 0x40000, v12
	v_add_u32_e32 v14, 0x800, v14
	global_load_dword v45, v12, s[4:5]
	global_load_dwordx2 v[58:59], v14, s[8:9]
	v_add_u32_e32 v12, 0x40000, v12
	v_add_u32_e32 v14, 0x800, v14
	global_load_dword v46, v12, s[4:5]
	global_load_dwordx2 v[60:61], v14, s[8:9]
	v_add_u32_e32 v12, 0x40000, v12
	v_add_u32_e32 v14, 0x800, v14
	global_load_dword v47, v12, s[4:5]
	global_load_dwordx2 v[62:63], v14, s[8:9]
	v_add_u32_e32 v12, 0x40000, v12
	v_add_u32_e32 v14, 0x800, v14
	s_waitcnt vmcnt(16)
	v_cvt_pk_bf16_f32 v15, v6, v7
	global_store_dword v13, v15, s[6:7]
	v_add_u32_e32 v13, 0x40000, v13
	v_lshlrev_b32_e32 v4, 16, v16
	v_and_b32_e32 v5, 0xffff0000, v16
	v_pk_fma_f32 v[6:7], v[6:7], v[24:25], v[4:5]
	v_cvt_pk_bf16_f32 v64, v6, v7
	global_store_dword v13, v64, s[6:7]
	v_add_u32_e32 v13, 0x40000, v13
	v_lshlrev_b32_e32 v4, 16, v17
	v_and_b32_e32 v5, 0xffff0000, v17
	v_pk_fma_f32 v[6:7], v[6:7], v[26:27], v[4:5]
	v_cvt_pk_bf16_f32 v15, v6, v7
	global_store_dword v13, v15, s[6:7]
	v_add_u32_e32 v13, 0x40000, v13
	v_lshlrev_b32_e32 v4, 16, v18
	v_and_b32_e32 v5, 0xffff0000, v18
	v_pk_fma_f32 v[6:7], v[6:7], v[28:29], v[4:5]
	v_cvt_pk_bf16_f32 v64, v6, v7
	global_store_dword v13, v64, s[6:7]
	v_add_u32_e32 v13, 0x40000, v13
	v_lshlrev_b32_e32 v4, 16, v19
	v_and_b32_e32 v5, 0xffff0000, v19
	v_pk_fma_f32 v[6:7], v[6:7], v[30:31], v[4:5]
	v_cvt_pk_bf16_f32 v15, v6, v7
	global_store_dword v13, v15, s[6:7]
	v_add_u32_e32 v13, 0x40000, v13
	v_lshlrev_b32_e32 v4, 16, v20
	v_and_b32_e32 v5, 0xffff0000, v20
	v_pk_fma_f32 v[6:7], v[6:7], v[32:33], v[4:5]
	v_cvt_pk_bf16_f32 v64, v6, v7
	global_store_dword v13, v64, s[6:7]
	v_add_u32_e32 v13, 0x40000, v13
	v_lshlrev_b32_e32 v4, 16, v21
	v_and_b32_e32 v5, 0xffff0000, v21
	v_pk_fma_f32 v[6:7], v[6:7], v[34:35], v[4:5]
	v_cvt_pk_bf16_f32 v15, v6, v7
	global_store_dword v13, v15, s[6:7]
	v_add_u32_e32 v13, 0x40000, v13
	v_lshlrev_b32_e32 v4, 16, v22
	v_and_b32_e32 v5, 0xffff0000, v22
	v_pk_fma_f32 v[6:7], v[6:7], v[36:37], v[4:5]
	v_cvt_pk_bf16_f32 v64, v6, v7
	global_store_dword v13, v64, s[6:7]
	v_add_u32_e32 v13, 0x40000, v13
	v_lshlrev_b32_e32 v4, 16, v23
	v_and_b32_e32 v5, 0xffff0000, v23
	v_pk_fma_f32 v[6:7], v[6:7], v[38:39], v[4:5]
	s_cmp_eq_u32 s16, 7
	s_cbranch_scc1 .Lg2_tail
	global_load_dword v16, v12, s[4:5]
	global_load_dwordx2 v[24:25], v14, s[8:9]
	v_add_u32_e32 v12, 0x40000, v12
	v_add_u32_e32 v14, 0x800, v14
	global_load_dword v17, v12, s[4:5]
	global_load_dwordx2 v[26:27], v14, s[8:9]
	v_add_u32_e32 v12, 0x40000, v12
	v_add_u32_e32 v14, 0x800, v14
	global_load_dword v18, v12, s[4:5]
	global_load_dwordx2 v[28:29], v14, s[8:9]
	v_add_u32_e32 v12, 0x40000, v12
	v_add_u32_e32 v14, 0x800, v14
	global_load_dword v19, v12, s[4:5]
	global_load_dwordx2 v[30:31], v14, s[8:9]
	v_add_u32_e32 v12, 0x40000, v12
	v_add_u32_e32 v14, 0x800, v14
	global_load_dword v20, v12, s[4:5]
	global_load_dwordx2 v[32:33], v14, s[8:9]
	v_add_u32_e32 v12, 0x40000, v12
	v_add_u32_e32 v14, 0x800, v14
	global_load_dword v21, v12, s[4:5]
	global_load_dwordx2 v[34:35], v14, s[8:9]
	v_add_u32_e32 v12, 0x40000, v12
	v_add_u32_e32 v14, 0x800, v14
	global_load_dword v22, v12, s[4:5]
	global_load_dwordx2 v[36:37], v14, s[8:9]
	v_add_u32_e32 v12, 0x40000, v12
	v_add_u32_e32 v14, 0x800, v14
	global_load_dword v23, v12, s[4:5]
	global_load_dwordx2 v[38:39], v14, s[8:9]
	v_add_u32_e32 v12, 0x40000, v12
	v_add_u32_e32 v14, 0x800, v14
	s_waitcnt vmcnt(16)
	v_cvt_pk_bf16_f32 v15, v6, v7
	global_store_dword v13, v15, s[6:7]
	v_add_u32_e32 v13, 0x40000, v13
	v_lshlrev_b32_e32 v4, 16, v40
	v_and_b32_e32 v5, 0xffff0000, v40
	v_pk_fma_f32 v[6:7], v[6:7], v[48:49], v[4:5]
	v_cvt_pk_bf16_f32 v64, v6, v7
	global_store_dword v13, v64, s[6:7]
	v_add_u32_e32 v13, 0x40000, v13
	v_lshlrev_b32_e32 v4, 16, v41
	v_and_b32_e32 v5, 0xffff0000, v41
	v_pk_fma_f32 v[6:7], v[6:7], v[50:51], v[4:5]
	v_cvt_pk_bf16_f32 v15, v6, v7
	global_store_dword v13, v15, s[6:7]
	v_add_u32_e32 v13, 0x40000, v13
	v_lshlrev_b32_e32 v4, 16, v42
	v_and_b32_e32 v5, 0xffff0000, v42
	v_pk_fma_f32 v[6:7], v[6:7], v[52:53], v[4:5]
	v_cvt_pk_bf16_f32 v64, v6, v7
	global_store_dword v13, v64, s[6:7]
	v_add_u32_e32 v13, 0x40000, v13
	v_lshlrev_b32_e32 v4, 16, v43
	v_and_b32_e32 v5, 0xffff0000, v43
	v_pk_fma_f32 v[6:7], v[6:7], v[54:55], v[4:5]
	v_cvt_pk_bf16_f32 v15, v6, v7
	global_store_dword v13, v15, s[6:7]
	v_add_u32_e32 v13, 0x40000, v13
	v_lshlrev_b32_e32 v4, 16, v44
	v_and_b32_e32 v5, 0xffff0000, v44
	v_pk_fma_f32 v[6:7], v[6:7], v[56:57], v[4:5]
	v_cvt_pk_bf16_f32 v64, v6, v7
	global_store_dword v13, v64, s[6:7]
	v_add_u32_e32 v13, 0x40000, v13
	v_lshlrev_b32_e32 v4, 16, v45
	v_and_b32_e32 v5, 0xffff0000, v45
	v_pk_fma_f32 v[6:7], v[6:7], v[58:59], v[4:5]
	v_cvt_pk_bf16_f32 v15, v6, v7
	global_store_dword v13, v15, s[6:7]
	v_add_u32_e32 v13, 0x40000, v13
	v_lshlrev_b32_e32 v4, 16, v46
	v_and_b32_e32 v5, 0xffff0000, v46
	v_pk_fma_f32 v[6:7], v[6:7], v[60:61], v[4:5]
	v_cvt_pk_bf16_f32 v64, v6, v7
	global_store_dword v13, v64, s[6:7]
	v_add_u32_e32 v13, 0x40000, v13
	v_lshlrev_b32_e32 v4, 16, v47
	v_and_b32_e32 v5, 0xffff0000, v47
	v_pk_fma_f32 v[6:7], v[6:7], v[62:63], v[4:5]
	s_add_i32 s16, s16, 1
	s_branch .Lg2_loop
.Lg2_tail:
	s_waitcnt vmcnt(0)
	v_cvt_pk_bf16_f32 v15, v6, v7
	global_store_dword v13, v15, s[6:7]
	v_add_u32_e32 v13, 0x40000, v13
	v_lshlrev_b32_e32 v4, 16, v40
	v_and_b32_e32 v5, 0xffff0000, v40
	v_pk_fma_f32 v[6:7], v[6:7], v[48:49], v[4:5]
	v_cvt_pk_bf16_f32 v64, v6, v7
	global_store_dword v13, v64, s[6:7]
	v_add_u32_e32 v13, 0x40000, v13
	v_lshlrev_b32_e32 v4, 16, v41
	v_and_b32_e32 v5, 0xffff0000, v41
	v_pk_fma_f32 v[6:7], v[6:7], v[50:51], v[4:5]
	v_cvt_pk_bf16_f32 v15, v6, v7
	global_store_dword v13, v15, s[6:7]
	v_add_u32_e32 v13, 0x40000, v13
	v_lshlrev_b32_e32 v4, 16, v42
	v_and_b32_e32 v5, 0xffff0000, v42
	v_pk_fma_f32 v[6:7], v[6:7], v[52:53], v[4:5]
	v_cvt_pk_bf16_f32 v64, v6, v7
	global_store_dword v13, v64, s[6:7]
	v_add_u32_e32 v13, 0x40000, v13
	v_lshlrev_b32_e32 v4, 16, v43
	v_and_b32_e32 v5, 0xffff0000, v43
	v_pk_fma_f32 v[6:7], v[6:7], v[54:55], v[4:5]
	v_cvt_pk_bf16_f32 v15, v6, v7
	global_store_dword v13, v15, s[6:7]
	v_add_u32_e32 v13, 0x40000, v13
	v_lshlrev_b32_e32 v4, 16, v44
	v_and_b32_e32 v5, 0xffff0000, v44
	v_pk_fma_f32 v[6:7], v[6:7], v[56:57], v[4:5]
	v_cvt_pk_bf16_f32 v64, v6, v7
	global_store_dword v13, v64, s[6:7]
	v_add_u32_e32 v13, 0x40000, v13
	v_lshlrev_b32_e32 v4, 16, v45
	v_and_b32_e32 v5, 0xffff0000, v45
	v_pk_fma_f32 v[6:7], v[6:7], v[58:59], v[4:5]
	v_cvt_pk_bf16_f32 v15, v6, v7
	global_store_dword v13, v15, s[6:7]
	v_add_u32_e32 v13, 0x40000, v13
	v_lshlrev_b32_e32 v4, 16, v46
	v_and_b32_e32 v5, 0xffff0000, v46
	v_pk_fma_f32 v[6:7], v[6:7], v[60:61], v[4:5]
	v_cvt_pk_bf16_f32 v64, v6, v7
	global_store_dword v13, v64, s[6:7]
	v_add_u32_e32 v13, 0x40000, v13
	v_lshlrev_b32_e32 v4, 16, v47
	v_and_b32_e32 v5, 0xffff0000, v47
	v_pk_fma_f32 v[6:7], v[6:7], v[62:63], v[4:5]
	v_lshl_or_b32 v4, v9, 7, v10
	v_ashrrev_i32_e32 v5, 31, v4
	v_lshlrev_b64 v[4:5], 10, v[4:5]
	v_add_u32_e32 v1, s14, v1
	v_lshl_add_u64 v[4:5], s[10:11], 0, v[4:5]
	v_lshlrev_b32_e32 v2, 2, v8
	v_cmp_lt_i32_e32 vcc, s15, v1
	v_lshl_add_u64 v[4:5], v[4:5], 0, v[2:3]
	s_or_b64 s[12:13], vcc, s[12:13]
	global_store_dword v[4:5], v6, off
	global_store_dword v[4:5], v7, off offset:1024
	s_andn2_b64 exec, exec, s[12:13]
	s_cbranch_execnz .LBB0_1200
